# GEMM main loops: the 8 B-fragment LDS reads of the iteration's first segment issued right after the A-fragment reads, ahead of the scalar pointer bookkeeping (pure reorder), on top of v59
# speedup vs baseline: 1.0053x; 1.0053x over previous
.LBB0_204:
	s_add_u32 s8, s6, 0xffdf0080
	s_addc_u32 s9, s7, -1
	s_cmp_eq_u32 s91, 12
	v_add_u32_e32 v142, 0x10000, v153
	v_add_u32_e32 v146, 0x14000, v153
	s_cselect_b32 s56, s50, s8
	ds_read_b128 v[130:133], v142
	ds_read_b128 v[134:137], v142 offset:1024
	ds_read_b128 v[138:141], v142 offset:2048
	ds_read_b128 v[142:145], v142 offset:3072
	ds_read_b128 v[182:185], v146
	ds_read_b128 v[186:189], v146 offset:1024
	ds_read_b128 v[190:193], v146 offset:2048
	ds_read_b128 v[210:213], v146 offset:3072
	ds_read_b128 v[214:217], v154
	ds_read_b128 v[218:221], v154 offset:1024
	ds_read_b128 v[222:225], v154 offset:2048
	ds_read_b128 v[226:229], v154 offset:3072
	ds_read_b128 v[230:233], v154 offset:4096
	ds_read_b128 v[234:237], v154 offset:5120
	ds_read_b128 v[238:241], v154 offset:6144
	ds_read_b128 v[242:245], v154 offset:7168
	s_cselect_b32 s57, s51, s9
	s_cselect_b32 s39, s47, s31
	s_cselect_b32 s38, s49, s5
	s_add_u32 s34, s56, 0x80
	s_addc_u32 s35, s57, 0
	s_cmp_eq_u32 s91, -2
	s_cselect_b64 s[8:9], -1, 0
	s_and_b64 s[8:9], s[0:1], s[8:9]
	v_cndmask_b32_e64 v146, 0, 1, s[8:9]
	s_add_u32 s54, s38, 0x80
	v_readfirstlane_b32 s8, v146
	s_addc_u32 s55, s39, 0
	s_and_b32 s18, s8, 1
	s_cmp_lg_u32 s18, 0
	s_cbranch_scc1 .Lst_skip_5
	s_mov_b32 m0, s72
	s_nop 0
	global_load_lds_dwordx4 v0, s[6:7]

.LBB0_373:
	s_add_u32 s8, s40, 0xfffc0080
	s_addc_u32 s9, s41, -1
	v_add_u32_e32 v147, 0x10000, v145
	s_cmp_eq_u32 s78, 12
	ds_read_b128 v[130:133], v147
	ds_read_b128 v[148:151], v147 offset:1024
	ds_read_b128 v[152:155], v147 offset:2048
	ds_read_b128 v[182:185], v147 offset:3072
	v_add_u32_e32 v147, 0x14000, v145
	s_cselect_b32 s50, s75, s8
	ds_read_b128 v[186:189], v147
	ds_read_b128 v[190:193], v147 offset:1024
	ds_read_b128 v[210:213], v147 offset:2048
	ds_read_b128 v[214:217], v147 offset:3072
	ds_read_b128 v[218:221], v146
	ds_read_b128 v[222:225], v146 offset:1024
	ds_read_b128 v[226:229], v146 offset:2048
	ds_read_b128 v[230:233], v146 offset:3072
	ds_read_b128 v[234:237], v146 offset:4096
	ds_read_b128 v[238:241], v146 offset:5120
	ds_read_b128 v[242:245], v146 offset:6144
	ds_read_b128 v[246:249], v146 offset:7168
	s_cselect_b32 s51, s23, s9
	s_cselect_b32 s47, s25, s77
	s_cselect_b32 s46, s31, s76
	s_add_u32 s42, s50, 0x80
	s_addc_u32 s43, s51, 0
	s_cmp_eq_u32 s78, -2
	s_cselect_b64 s[8:9], -1, 0
	s_and_b64 s[8:9], s[44:45], s[8:9]
	v_cndmask_b32_e64 v147, 0, 1, s[8:9]
	s_add_u32 s48, s46, 0x80
	v_readfirstlane_b32 s8, v147
	s_addc_u32 s49, s47, 0
	s_and_b32 s18, s8, 1
	s_cmp_lg_u32 s18, 0
	s_cbranch_scc1 .Lst_skip_10
	s_mov_b32 m0, s69
	s_nop 0
	global_load_lds_dwordx4 v136, s[40:41]

.LBB0_459:
	s_add_u32 s8, s40, 0xfffc0080
	s_addc_u32 s9, s41, -1
	v_add_u32_e32 v130, 0x10000, v142
	s_cmp_eq_u32 s75, 12
	ds_read_b128 v[144:147], v130
	ds_read_b128 v[148:151], v130 offset:1024
	ds_read_b128 v[152:155], v130 offset:2048
	ds_read_b128 v[182:185], v130 offset:3072
	v_add_u32_e32 v130, 0x14000, v142
	s_cselect_b32 s50, s71, s8
	ds_read_b128 v[186:189], v130
	ds_read_b128 v[190:193], v130 offset:1024
	ds_read_b128 v[210:213], v130 offset:2048
	ds_read_b128 v[214:217], v130 offset:3072
	ds_read_b128 v[218:221], v143
	ds_read_b128 v[222:225], v143 offset:1024
	ds_read_b128 v[226:229], v143 offset:2048
	ds_read_b128 v[230:233], v143 offset:3072
	ds_read_b128 v[234:237], v143 offset:4096
	ds_read_b128 v[238:241], v143 offset:5120
	ds_read_b128 v[242:245], v143 offset:6144
	ds_read_b128 v[246:249], v143 offset:7168
	s_cselect_b32 s51, s27, s9
	s_cselect_b32 s47, s25, s74
	s_cselect_b32 s46, s31, s72
	s_add_u32 s42, s50, 0x80
	s_addc_u32 s43, s51, 0
	s_cmp_eq_u32 s75, -2
	s_cselect_b64 s[8:9], -1, 0
	s_and_b64 s[8:9], s[44:45], s[8:9]
	v_cndmask_b32_e64 v130, 0, 1, s[8:9]
	s_add_u32 s48, s46, 0x80
	v_readfirstlane_b32 s8, v130
	s_addc_u32 s49, s47, 0
	s_and_b32 s18, s8, 1
	s_cmp_lg_u32 s18, 0
	s_cbranch_scc1 .Lst_skip_15
	s_mov_b32 m0, s66
	s_nop 0
	global_load_lds_dwordx4 v136, s[40:41]

.LBB0_489:
	s_add_u32 s8, s42, 0xfffc0080
	s_addc_u32 s9, s43, -1
	v_add_u32_e32 v0, 0x10000, v142
	s_cmp_eq_u32 s79, 12
	ds_read_b128 v[130:133], v0
	ds_read_b128 v[144:147], v0 offset:1024
	ds_read_b128 v[148:151], v0 offset:2048
	ds_read_b128 v[152:155], v0 offset:3072
	v_add_u32_e32 v0, 0x14000, v142
	s_cselect_b32 s52, s27, s8
	ds_read_b128 v[182:185], v0
	ds_read_b128 v[186:189], v0 offset:1024
	ds_read_b128 v[190:193], v0 offset:2048
	ds_read_b128 v[210:213], v0 offset:3072
	ds_read_b128 v[214:217], v143
	ds_read_b128 v[218:221], v143 offset:1024
	ds_read_b128 v[222:225], v143 offset:2048
	ds_read_b128 v[226:229], v143 offset:3072
	ds_read_b128 v[230:233], v143 offset:4096
	ds_read_b128 v[234:237], v143 offset:5120
	ds_read_b128 v[238:241], v143 offset:6144
	ds_read_b128 v[242:245], v143 offset:7168
	s_cselect_b32 s53, s1, s9
	s_cselect_b32 s49, s25, s78
	s_cselect_b32 s48, s31, s35
	s_add_u32 s44, s52, 0x80
	s_addc_u32 s45, s53, 0
	s_cmp_eq_u32 s79, -2
	s_cselect_b64 s[8:9], -1, 0
	s_and_b64 s[8:9], s[46:47], s[8:9]
	v_cndmask_b32_e64 v0, 0, 1, s[8:9]
	s_add_u32 s50, s48, 0x80
	v_readfirstlane_b32 s8, v0
	s_addc_u32 s51, s49, 0
	s_and_b32 s18, s8, 1
	s_cmp_lg_u32 s18, 0
	s_cbranch_scc1 .Lst_skip_20
	s_mov_b32 m0, s74
	s_nop 0
	global_load_lds_dwordx4 v136, s[42:43]

.LBB0_606:
	s_add_u32 s8, s38, 0xfffc0080
	s_addc_u32 s9, s39, -1
	v_add_u32_e32 v130, 0x10000, v138
	s_cmp_eq_u32 s74, 12
	ds_read_b128 v[140:143], v130
	ds_read_b128 v[144:147], v130 offset:1024
	ds_read_b128 v[148:151], v130 offset:2048
	ds_read_b128 v[152:155], v130 offset:3072
	v_add_u32_e32 v130, 0x14000, v138
	s_cselect_b32 s48, s70, s8
	ds_read_b128 v[182:185], v130
	ds_read_b128 v[186:189], v130 offset:1024
	ds_read_b128 v[190:193], v130 offset:2048
	ds_read_b128 v[210:213], v130 offset:3072
	ds_read_b128 v[214:217], v139
	ds_read_b128 v[218:221], v139 offset:1024
	ds_read_b128 v[222:225], v139 offset:2048
	ds_read_b128 v[226:229], v139 offset:3072
	ds_read_b128 v[230:233], v139 offset:4096
	ds_read_b128 v[234:237], v139 offset:5120
	ds_read_b128 v[238:241], v139 offset:6144
	ds_read_b128 v[242:245], v139 offset:7168
	s_cselect_b32 s49, s25, s9
	s_cselect_b32 s45, s23, s72
	s_cselect_b32 s44, s71, s31
	s_add_u32 s40, s48, 0x80
	s_addc_u32 s41, s49, 0
	s_cmp_eq_u32 s74, -2
	s_cselect_b64 s[8:9], -1, 0
	s_and_b64 s[8:9], s[42:43], s[8:9]
	v_cndmask_b32_e64 v130, 0, 1, s[8:9]
	s_add_u32 s46, s44, 0x80
	v_readfirstlane_b32 s8, v130
	s_addc_u32 s47, s45, 0
	s_and_b32 s18, s8, 1
	s_cmp_lg_u32 s18, 0
	s_cbranch_scc1 .Lst_skip_25
	s_mov_b32 m0, s65
	s_nop 0
	global_load_lds_dwordx4 v0, s[38:39]
